# static s_setprio 1 for waves 0-3 (mirror of the previous), per-segment flips deleted
# baseline (speedup 1.0000x reference)
_Z10fwd_kernel4Args:
	s_load_dword s97, s[0:1], 0xa0
	s_mov_b32 s8, s2
	s_add_u32 s2, s0, 0xa0
	s_addc_u32 s3, s1, 0
	v_lshl_add_u32 v1, v0, 2, 0
	v_writelane_b32 v254, s2, 0
	v_add_u32_e32 v1, 0x20000, v1
	v_mov_b32_e32 v2, 0
	v_readfirstlane_b32 s9, v0
	v_writelane_b32 v254, s3, 1
	ds_write2st64_b32 v1, v2, v2 offset1:8
	ds_write2st64_b32 v1, v2, v2 offset0:16 offset1:24
	v_or_b32_e32 v1, 0x800, v0
	s_mov_b64 s[2:3], -1
	s_and_saveexec_b64 s[4:5], s[2:3]
	v_lshl_add_u32 v3, v1, 2, 0
	v_add_u32_e32 v3, 0x20000, v3
	ds_write_b32 v3, v2
	s_or_b64 exec, exec, s[4:5]
	s_and_saveexec_b64 s[4:5], s[2:3]
	s_add_i32 s2, 0, 0x20000
	v_lshl_add_u32 v1, v1, 2, s2
	v_mov_b32_e32 v2, 0
	ds_write_b32 v1, v2 offset:2048
	s_or_b64 exec, exec, s[4:5]
	v_or_b32_e32 v1, 0xc00, v0
	v_cmp_gt_u32_e64 s[2:3], 7, 6
	v_cmp_gt_u32_e64 s[6:7], 7, 5
	s_and_saveexec_b64 s[4:5], s[6:7]
	v_lshl_add_u32 v2, v1, 2, 0
	v_add_u32_e32 v2, 0x20000, v2
	v_mov_b32_e32 v3, 0
	ds_write_b32 v2, v3
	s_or_b64 exec, exec, s[4:5]
	s_load_dwordx8 s[88:95], s[0:1], 0x80
	s_and_saveexec_b64 s[4:5], s[2:3]
	s_add_i32 s2, 0, 0x20000
	v_lshl_add_u32 v1, v1, 2, s2
	v_mov_b32_e32 v2, 0
	ds_write_b32 v1, v2 offset:2048
	s_or_b64 exec, exec, s[4:5]
	s_load_dwordx16 s[12:27], s[0:1], 0x0
	s_waitcnt lgkmcnt(0)
	s_barrier
	s_cmp_ge_u32 s9, 0x100
	s_cbranch_scc1 .Lmy_prio_done
	s_setprio 1
